# adds: static s_setprio 1 for waves 4-7 and flip deletion also in the branch GEMM K-loop (all four GEMM loops now)
# speedup vs baseline: 1.0055x; 1.0045x over previous
; #define GAS __attribute__((address_space(1)))
; __device__ __forceinline__ unsigned cvt_pk_bf16(float lo, float hi) { const f32x2_t_ v = {lo, hi}; const bf16x2_t_ b = __builtin_convertvector(v, bf16x2_t_); return __builtin_bit_cast(unsigned, b); }
; __device__ __forceinline__ void gate_mul4(f32x4& v, unsigned g) { const float s = 1.0f / 255.0f; v[0] *= ub0(g) * s; v[1] *= ub1(g) * s; v[2] *= ub2(g) * s; v[3] *= ub3(g) * s; }
;     __device__ __forceinline__ void operator()(const f32x4 (&acc)[2][2][4][2], const pg8::GUnit& u, int wr, int wc, int fr, int fq) const {
;         const int row0 = u.pm * 256 + wr * 64 + fr, col0 = u.pn * 256 + wc * 32 + 8 * fq;
;         GAS bf16_t* mp0 = (GAS bf16_t*)Mg + (size_t)row0 * DM + col0;
;     ...
;         const GAS unsigned char* gp = (const GAS unsigned char*)P + (size_t)(u.pm * 256 + (wr * 4 + wc) * 32 + fq) * (INW * 2) + (GA * 2 + (2 * 16 + u.pn) * 256 + fr * 16);
;         u32x4 g[8];
; #pragma unroll
;         for (int k = 0; k < 8; ++k) g[k] = *(const GAS u32x4*)(gp + (size_t)(k * 4) * (INW * 2));
; #pragma unroll
;         for (int k = 0; k < 8; ++k) { const int ai = k >> 2, m = k & 3;
; #pragma unroll
;             for (int bj = 0; bj < 2; ++bj) { f32x4 v0 = acc[ai][bj][m][0], v1 = acc[ai][bj][m][1];
;                 gate_mul4(v0, bj ? g[k].z : g[k].x); gate_mul4(v1, bj ? g[k].w : g[k].y);
;                 u32x4 w; w.x = cvt_pk_bf16(v0[0], v0[1]); w.y = cvt_pk_bf16(v0[2], v0[3]); w.z = cvt_pk_bf16(v1[0], v1[1]); w.w = cvt_pk_bf16(v1[2], v1[3]);
;                 *(GAS u32x4*)(mp0 + (size_t)(ai * 128 + m * 16) * DM + bj * 128) = w; } }
.LBB0_777:
	s_setprio 0
	v_mbcnt_lo_u32_b32 v0, -1, 0
	v_mbcnt_hi_u32_b32 v0, -1, v0
	s_add_i32 s83, s83, s3
	v_and_b32_e32 v134, 15, v0
	v_ashrrev_i32_e32 v0, 4, v0
	s_or_b32 s8, s82, s1
	s_add_i32 s82, s82, 0x8000
	v_or_b32_e32 v2, s83, v134
	v_lshl_add_u32 v164, v0, 3, s8
	v_add_u32_e32 v0, s84, v0
	v_lshl_or_b32 v134, v134, 4, s82
	v_mad_i64_i32 v[132:133], s[8:9], v0, s93, v[200:201]
	v_ashrrev_i32_e32 v135, 31, v134
	v_lshl_add_u64 v[136:137], v[132:133], 0, v[134:135]
	v_add_co_u32_e32 v132, vcc, s48, v136
	s_mov_b32 s9, 0x60000
	s_nop 0
	v_addc_co_u32_e32 v133, vcc, 0, v137, vcc
	v_add_co_u32_e32 v132, vcc, s9, v136
	s_mov_b32 s8, 0x90000
	s_nop 0
	v_addc_co_u32_e32 v133, vcc, 0, v137, vcc
	v_add_co_u32_e32 v132, vcc, s8, v136
	v_ashrrev_i32_e32 v3, 31, v2
	s_nop 0
	v_addc_co_u32_e32 v133, vcc, 0, v137, vcc
	s_mov_b32 s8, 0xc0000
	v_lshlrev_b64 v[2:3], 13, v[2:3]
	v_add_co_u32_e32 v132, vcc, s8, v136
	v_ashrrev_i32_e32 v165, 31, v164
	s_nop 0
	v_addc_co_u32_e32 v133, vcc, 0, v137, vcc
	v_lshl_add_u64 v[2:3], v[198:199], 0, v[2:3]
	v_lshl_add_u64 v[2:3], v[164:165], 1, v[2:3]
	s_mov_b32 s8, 0xf0000
	v_add_co_u32_e32 v132, vcc, s8, v136
	s_mov_b32 s10, 0x120000
	s_nop 0
	v_addc_co_u32_e32 v133, vcc, 0, v137, vcc
	v_add_co_u32_e32 v132, vcc, s10, v136
	s_mov_b32 s8, 0x150000
	s_nop 0
	v_addc_co_u32_e32 v133, vcc, 0, v137, vcc
	v_add_co_u32_e32 v136, vcc, s8, v136
	s_nop 0
	v_addc_co_u32_e32 v137, vcc, 0, v137, vcc
	s_mov_b32 s8, 0x40000
	s_mov_b32 s26, 0x60000
	s_mov_b32 s27, 0x120000
	s_mov_b32 s86, s46
	v_mov_b32_e32 v160, v215
	v_mov_b32_e32 v161, v216
	v_mov_b32_e32 v162, v217
	v_mov_b32_e32 v163, v218
	v_mov_b32_e32 v156, v219
	v_mov_b32_e32 v157, v220
	v_mov_b32_e32 v158, v221
	v_mov_b32_e32 v159, v222
	v_mov_b32_e32 v152, v223
	v_mov_b32_e32 v153, v224
	v_mov_b32_e32 v154, v225
	v_mov_b32_e32 v155, v226
	v_mov_b32_e32 v148, v227
	v_mov_b32_e32 v149, v228
	v_mov_b32_e32 v150, v229
	v_mov_b32_e32 v151, v230
	v_mov_b32_e32 v144, v231
	v_mov_b32_e32 v145, v232
	v_mov_b32_e32 v146, v233
	v_mov_b32_e32 v147, v234
	v_mov_b32_e32 v140, v235
	v_mov_b32_e32 v141, v236
	v_mov_b32_e32 v142, v237
	v_mov_b32_e32 v143, v238
	v_mov_b32_e32 v132, v239
	v_mov_b32_e32 v133, v240
	v_mov_b32_e32 v134, v241
	v_mov_b32_e32 v135, v242
	v_mov_b32_e32 v136, v243
	v_mov_b32_e32 v137, v245
	v_mov_b32_e32 v138, v246
	v_mov_b32_e32 v139, v247
	s_waitcnt vmcnt(0)
	v_cvt_f32_ubyte1_e32 v165, v160
	v_cvt_f32_ubyte0_e32 v164, v160
	v_pk_mul_f32 v[164:165], v[164:165], s[6:7] op_sel_hi:[1,0]
	s_nop 0
	v_pk_mul_f32 v[128:129], v[128:129], v[164:165]
	v_cvt_f32_ubyte3_e32 v165, v160
	v_cvt_f32_ubyte2_e32 v164, v160
	v_pk_mul_f32 v[164:165], v[164:165], s[6:7] op_sel_hi:[1,0]
	s_nop 0
	v_pk_mul_f32 v[130:131], v[130:131], v[164:165]
	v_cvt_f32_ubyte1_e32 v165, v161
	v_cvt_f32_ubyte0_e32 v164, v161
	v_pk_mul_f32 v[164:165], v[164:165], s[6:7] op_sel_hi:[1,0]
	s_nop 0
	v_pk_mul_f32 v[164:165], v[124:125], v[164:165]
	v_cvt_f32_ubyte3_e32 v125, v161
	v_cvt_f32_ubyte2_e32 v124, v161
	v_pk_mul_f32 v[124:125], v[124:125], s[6:7] op_sel_hi:[1,0]
	s_nop 0
	v_pk_mul_f32 v[160:161], v[126:127], v[124:125]
	v_cvt_pk_bf16_f32 v124, v128, v129
	v_cvt_pk_bf16_f32 v125, v130, v131
	v_cvt_pk_bf16_f32 v126, v164, v165
	v_cvt_pk_bf16_f32 v127, v160, v161
	global_store_dwordx4 v[2:3], v[124:127], off
	s_nop 1
	v_cvt_f32_ubyte1_e32 v125, v162
	v_cvt_f32_ubyte0_e32 v124, v162
	v_pk_mul_f32 v[124:125], v[124:125], s[6:7] op_sel_hi:[1,0]
	s_nop 0
	v_pk_mul_f32 v[120:121], v[120:121], v[124:125]
	v_cvt_f32_ubyte3_e32 v125, v162
	v_cvt_f32_ubyte2_e32 v124, v162
	v_pk_mul_f32 v[124:125], v[124:125], s[6:7] op_sel_hi:[1,0]
	s_nop 0
	v_pk_mul_f32 v[122:123], v[122:123], v[124:125]
	v_cvt_f32_ubyte1_e32 v125, v163
	v_cvt_f32_ubyte0_e32 v124, v163
	v_pk_mul_f32 v[124:125], v[124:125], s[6:7] op_sel_hi:[1,0]
	s_nop 0
	v_pk_mul_f32 v[124:125], v[116:117], v[124:125]
	v_cvt_f32_ubyte3_e32 v117, v163
	v_cvt_f32_ubyte2_e32 v116, v163
	v_pk_mul_f32 v[116:117], v[116:117], s[6:7] op_sel_hi:[1,0]
	s_nop 0
	v_pk_mul_f32 v[126:127], v[118:119], v[116:117]
	v_cvt_pk_bf16_f32 v116, v120, v121
	v_cvt_pk_bf16_f32 v117, v122, v123
	v_cvt_pk_bf16_f32 v118, v124, v125
	v_cvt_pk_bf16_f32 v119, v126, v127
	global_store_dwordx4 v[2:3], v[116:119], off offset:256
	s_nop 1
	v_cvt_f32_ubyte1_e32 v117, v156
	v_cvt_f32_ubyte0_e32 v116, v156
	v_pk_mul_f32 v[116:117], v[116:117], s[6:7] op_sel_hi:[1,0]
	s_nop 0
	v_pk_mul_f32 v[112:113], v[112:113], v[116:117]
	v_cvt_f32_ubyte3_e32 v117, v156
	v_cvt_f32_ubyte2_e32 v116, v156
	v_pk_mul_f32 v[116:117], v[116:117], s[6:7] op_sel_hi:[1,0]
	s_nop 0
	v_pk_mul_f32 v[114:115], v[114:115], v[116:117]
	v_cvt_f32_ubyte1_e32 v117, v157
	v_cvt_f32_ubyte0_e32 v116, v157
	v_pk_mul_f32 v[116:117], v[116:117], s[6:7] op_sel_hi:[1,0]
	s_nop 0
	v_pk_mul_f32 v[116:117], v[108:109], v[116:117]
	v_cvt_f32_ubyte3_e32 v109, v157
	v_cvt_f32_ubyte2_e32 v108, v157
	v_pk_mul_f32 v[108:109], v[108:109], s[6:7] op_sel_hi:[1,0]
	s_nop 0
	v_pk_mul_f32 v[118:119], v[110:111], v[108:109]
	v_cvt_pk_bf16_f32 v108, v112, v113
	v_add_co_u32_e32 v112, vcc, s29, v2
	v_cvt_pk_bf16_f32 v109, v114, v115
	v_cvt_pk_bf16_f32 v110, v116, v117
	v_cvt_pk_bf16_f32 v111, v118, v119
	v_addc_co_u32_e32 v113, vcc, 0, v3, vcc
	global_store_dwordx4 v[112:113], v[108:111], off
	s_nop 1
	v_cvt_f32_ubyte1_e32 v109, v158
	v_cvt_f32_ubyte0_e32 v108, v158
	v_pk_mul_f32 v[108:109], v[108:109], s[6:7] op_sel_hi:[1,0]
	s_nop 0
	v_pk_mul_f32 v[104:105], v[104:105], v[108:109]
	v_cvt_f32_ubyte3_e32 v109, v158
	v_cvt_f32_ubyte2_e32 v108, v158
	v_pk_mul_f32 v[108:109], v[108:109], s[6:7] op_sel_hi:[1,0]
	s_nop 0
; #define GAS __attribute__((address_space(1)))
; __device__ __forceinline__ unsigned cvt_pk_bf16(float lo, float hi) { const f32x2_t_ v = {lo, hi}; const bf16x2_t_ b = __builtin_convertvector(v, bf16x2_t_); return __builtin_bit_cast(unsigned, b); }
; __device__ __forceinline__ void gate_mul4(f32x4& v, unsigned g) { const float s = 1.0f / 255.0f; v[0] *= ub0(g) * s; v[1] *= ub1(g) * s; v[2] *= ub2(g) * s; v[3] *= ub3(g) * s; }
;     __device__ __forceinline__ void operator()(const f32x4 (&acc)[2][2][4][2], const pg8::GUnit& u, int wr, int wc, int fr, int fq) const {
;     ...
;         for (int k = 0; k < 8; ++k) g[k] = *(const GAS u32x4*)(gp + (size_t)(k * 4) * (INW * 2));
; #pragma unroll
;         for (int k = 0; k < 8; ++k) { const int ai = k >> 2, m = k & 3;
; #pragma unroll
;             for (int bj = 0; bj < 2; ++bj) { f32x4 v0 = acc[ai][bj][m][0], v1 = acc[ai][bj][m][1];
;                 gate_mul4(v0, bj ? g[k].z : g[k].x); gate_mul4(v1, bj ? g[k].w : g[k].y);
;                 u32x4 w; w.x = cvt_pk_bf16(v0[0], v0[1]); w.y = cvt_pk_bf16(v0[2], v0[3]); w.z = cvt_pk_bf16(v1[0], v1[1]); w.w = cvt_pk_bf16(v1[2], v1[3]);
;                 *(GAS u32x4*)(mp0 + (size_t)(ai * 128 + m * 16) * DM + bj * 128) = w; } }
	v_pk_mul_f32 v[106:107], v[106:107], v[108:109]
	v_cvt_f32_ubyte1_e32 v109, v159
	v_cvt_f32_ubyte0_e32 v108, v159
	v_pk_mul_f32 v[108:109], v[108:109], s[6:7] op_sel_hi:[1,0]
	s_nop 0
	v_pk_mul_f32 v[108:109], v[100:101], v[108:109]
	v_cvt_f32_ubyte3_e32 v101, v159
	v_cvt_f32_ubyte2_e32 v100, v159
	v_pk_mul_f32 v[100:101], v[100:101], s[6:7] op_sel_hi:[1,0]
	s_nop 0
	v_pk_mul_f32 v[110:111], v[102:103], v[100:101]
	v_cvt_pk_bf16_f32 v100, v104, v105
	v_cvt_pk_bf16_f32 v101, v106, v107
	v_cvt_pk_bf16_f32 v102, v108, v109
	v_cvt_pk_bf16_f32 v103, v110, v111
	global_store_dwordx4 v[112:113], v[100:103], off offset:256
	s_nop 1
	v_cvt_f32_ubyte1_e32 v101, v152
	v_cvt_f32_ubyte0_e32 v100, v152
	v_pk_mul_f32 v[100:101], v[100:101], s[6:7] op_sel_hi:[1,0]
	s_nop 0
	v_pk_mul_f32 v[96:97], v[96:97], v[100:101]
	v_cvt_f32_ubyte3_e32 v101, v152
	v_cvt_f32_ubyte2_e32 v100, v152
	v_pk_mul_f32 v[100:101], v[100:101], s[6:7] op_sel_hi:[1,0]
	s_nop 0
	v_pk_mul_f32 v[98:99], v[98:99], v[100:101]
	v_cvt_f32_ubyte1_e32 v101, v153
	v_cvt_f32_ubyte0_e32 v100, v153
	v_pk_mul_f32 v[100:101], v[100:101], s[6:7] op_sel_hi:[1,0]
	s_nop 0
	v_pk_mul_f32 v[100:101], v[92:93], v[100:101]
	v_cvt_f32_ubyte3_e32 v93, v153
	v_cvt_f32_ubyte2_e32 v92, v153
	v_pk_mul_f32 v[92:93], v[92:93], s[6:7] op_sel_hi:[1,0]
	s_nop 0
	v_pk_mul_f32 v[102:103], v[94:95], v[92:93]
	v_cvt_pk_bf16_f32 v92, v96, v97
	v_add_co_u32_e32 v96, vcc, s8, v2
	v_cvt_pk_bf16_f32 v93, v98, v99
	v_cvt_pk_bf16_f32 v94, v100, v101
	v_cvt_pk_bf16_f32 v95, v102, v103
	v_addc_co_u32_e32 v97, vcc, 0, v3, vcc
	global_store_dwordx4 v[96:97], v[92:95], off
	s_mov_b32 s8, 0x100000
	s_nop 0
	v_cvt_f32_ubyte1_e32 v93, v154
	v_cvt_f32_ubyte0_e32 v92, v154
	v_pk_mul_f32 v[92:93], v[92:93], s[6:7] op_sel_hi:[1,0]
	s_nop 0
	v_pk_mul_f32 v[88:89], v[88:89], v[92:93]
	v_cvt_f32_ubyte3_e32 v93, v154
	v_cvt_f32_ubyte2_e32 v92, v154
	v_pk_mul_f32 v[92:93], v[92:93], s[6:7] op_sel_hi:[1,0]
	s_nop 0
	v_pk_mul_f32 v[90:91], v[90:91], v[92:93]
	v_cvt_f32_ubyte1_e32 v93, v155
	v_cvt_f32_ubyte0_e32 v92, v155
	v_pk_mul_f32 v[92:93], v[92:93], s[6:7] op_sel_hi:[1,0]
	s_nop 0
	v_pk_mul_f32 v[92:93], v[84:85], v[92:93]
	v_cvt_f32_ubyte3_e32 v85, v155
	v_cvt_f32_ubyte2_e32 v84, v155
	v_pk_mul_f32 v[84:85], v[84:85], s[6:7] op_sel_hi:[1,0]
	s_nop 0
	v_pk_mul_f32 v[94:95], v[86:87], v[84:85]
	v_cvt_pk_bf16_f32 v84, v88, v89
	v_cvt_pk_bf16_f32 v85, v90, v91
	v_cvt_pk_bf16_f32 v86, v92, v93
	v_cvt_pk_bf16_f32 v87, v94, v95
	global_store_dwordx4 v[96:97], v[84:87], off offset:256
	s_nop 1
	v_cvt_f32_ubyte1_e32 v85, v148
	v_cvt_f32_ubyte0_e32 v84, v148
	v_pk_mul_f32 v[84:85], v[84:85], s[6:7] op_sel_hi:[1,0]
	s_nop 0
	v_pk_mul_f32 v[80:81], v[80:81], v[84:85]
	v_cvt_f32_ubyte3_e32 v85, v148
	v_cvt_f32_ubyte2_e32 v84, v148
	v_pk_mul_f32 v[84:85], v[84:85], s[6:7] op_sel_hi:[1,0]
	s_nop 0
	v_pk_mul_f32 v[82:83], v[82:83], v[84:85]
	v_cvt_f32_ubyte1_e32 v85, v149
	v_cvt_f32_ubyte0_e32 v84, v149
	v_pk_mul_f32 v[84:85], v[84:85], s[6:7] op_sel_hi:[1,0]
	s_nop 0
	v_pk_mul_f32 v[84:85], v[76:77], v[84:85]
	v_cvt_f32_ubyte3_e32 v77, v149
	v_cvt_f32_ubyte2_e32 v76, v149
	v_pk_mul_f32 v[76:77], v[76:77], s[6:7] op_sel_hi:[1,0]
	s_nop 0
	v_pk_mul_f32 v[86:87], v[78:79], v[76:77]
	v_cvt_pk_bf16_f32 v76, v80, v81
	v_add_co_u32_e32 v80, vcc, s9, v2
	v_cvt_pk_bf16_f32 v77, v82, v83
	v_cvt_pk_bf16_f32 v78, v84, v85
	v_cvt_pk_bf16_f32 v79, v86, v87
	v_addc_co_u32_e32 v81, vcc, 0, v3, vcc
	global_store_dwordx4 v[80:81], v[76:79], off
	s_mov_b32 s9, s13
	s_nop 0
	v_cvt_f32_ubyte1_e32 v77, v150
	v_cvt_f32_ubyte0_e32 v76, v150
	v_pk_mul_f32 v[76:77], v[76:77], s[6:7] op_sel_hi:[1,0]
	s_nop 0
	v_pk_mul_f32 v[72:73], v[72:73], v[76:77]
	v_cvt_f32_ubyte3_e32 v77, v150
	v_cvt_f32_ubyte2_e32 v76, v150
	v_pk_mul_f32 v[76:77], v[76:77], s[6:7] op_sel_hi:[1,0]
	s_nop 0
	v_pk_mul_f32 v[74:75], v[74:75], v[76:77]
	v_cvt_f32_ubyte1_e32 v77, v151
	v_cvt_f32_ubyte0_e32 v76, v151
	v_pk_mul_f32 v[76:77], v[76:77], s[6:7] op_sel_hi:[1,0]
	s_nop 0
	v_pk_mul_f32 v[76:77], v[68:69], v[76:77]
	v_cvt_f32_ubyte3_e32 v69, v151
	v_cvt_f32_ubyte2_e32 v68, v151
	v_pk_mul_f32 v[68:69], v[68:69], s[6:7] op_sel_hi:[1,0]
	s_nop 0
	v_pk_mul_f32 v[78:79], v[70:71], v[68:69]
	v_cvt_pk_bf16_f32 v68, v72, v73
	v_cvt_pk_bf16_f32 v69, v74, v75
	v_cvt_pk_bf16_f32 v70, v76, v77
	v_cvt_pk_bf16_f32 v71, v78, v79
	global_store_dwordx4 v[80:81], v[68:71], off offset:256
	s_nop 1
	v_cvt_f32_ubyte1_e32 v69, v144
	v_cvt_f32_ubyte0_e32 v68, v144
	v_pk_mul_f32 v[68:69], v[68:69], s[6:7] op_sel_hi:[1,0]
	s_nop 0
	v_pk_mul_f32 v[64:65], v[64:65], v[68:69]
	v_cvt_f32_ubyte3_e32 v69, v144
	v_cvt_f32_ubyte2_e32 v68, v144
	v_pk_mul_f32 v[68:69], v[68:69], s[6:7] op_sel_hi:[1,0]
	s_nop 0
	v_pk_mul_f32 v[66:67], v[66:67], v[68:69]
	v_cvt_f32_ubyte1_e32 v69, v145
	v_cvt_f32_ubyte0_e32 v68, v145
	v_pk_mul_f32 v[68:69], v[68:69], s[6:7] op_sel_hi:[1,0]
	s_nop 0
	v_pk_mul_f32 v[68:69], v[60:61], v[68:69]
	v_cvt_f32_ubyte3_e32 v61, v145
	v_cvt_f32_ubyte2_e32 v60, v145
	v_pk_mul_f32 v[60:61], v[60:61], s[6:7] op_sel_hi:[1,0]
	s_nop 0
	v_pk_mul_f32 v[70:71], v[62:63], v[60:61]
	v_cvt_pk_bf16_f32 v60, v64, v65
	v_add_co_u32_e32 v64, vcc, s8, v2
	v_cvt_pk_bf16_f32 v61, v66, v67
	v_cvt_pk_bf16_f32 v62, v68, v69
	v_cvt_pk_bf16_f32 v63, v70, v71
	v_addc_co_u32_e32 v65, vcc, 0, v3, vcc
	global_store_dwordx4 v[64:65], v[60:63], off
	s_mov_b32 s8, 0x140000
	s_nop 0
	v_cvt_f32_ubyte1_e32 v61, v146
	v_cvt_f32_ubyte0_e32 v60, v146
	v_pk_mul_f32 v[60:61], v[60:61], s[6:7] op_sel_hi:[1,0]
	s_nop 0
	v_pk_mul_f32 v[56:57], v[56:57], v[60:61]
	v_cvt_f32_ubyte3_e32 v61, v146
	v_cvt_f32_ubyte2_e32 v60, v146
	v_pk_mul_f32 v[60:61], v[60:61], s[6:7] op_sel_hi:[1,0]
; #define GAS __attribute__((address_space(1)))
; __device__ __forceinline__ unsigned cvt_pk_bf16(float lo, float hi) { const f32x2_t_ v = {lo, hi}; const bf16x2_t_ b = __builtin_convertvector(v, bf16x2_t_); return __builtin_bit_cast(unsigned, b); }
; __device__ __forceinline__ void gate_mul4(f32x4& v, unsigned g) { const float s = 1.0f / 255.0f; v[0] *= ub0(g) * s; v[1] *= ub1(g) * s; v[2] *= ub2(g) * s; v[3] *= ub3(g) * s; }
;     ...
;         const bool has_next = S.next(ui + 1, nxt);
;         const unsigned nA = has_next ? nxt.ao : cA, nB = has_next ? nxt.bo : cB;
;         const int nt = cur.nt;
;         for (int t = 0; t < nt; t += 2) {
;     __device__ __forceinline__ void operator()(const f32x4 (&acc)[2][2][4][2], const pg8::GUnit& u, int wr, int wc, int fr, int fq) const {
;     ...
;         for (int k = 0; k < 8; ++k) { const int ai = k >> 2, m = k & 3;
; #pragma unroll
;             for (int bj = 0; bj < 2; ++bj) { f32x4 v0 = acc[ai][bj][m][0], v1 = acc[ai][bj][m][1];
;                 gate_mul4(v0, bj ? g[k].z : g[k].x); gate_mul4(v1, bj ? g[k].w : g[k].y);
;                 u32x4 w; w.x = cvt_pk_bf16(v0[0], v0[1]); w.y = cvt_pk_bf16(v0[2], v0[3]); w.z = cvt_pk_bf16(v1[0], v1[1]); w.w = cvt_pk_bf16(v1[2], v1[3]);
;                 *(GAS u32x4*)(mp0 + (size_t)(ai * 128 + m * 16) * DM + bj * 128) = w; } }
	s_nop 0
	v_pk_mul_f32 v[58:59], v[58:59], v[60:61]
	v_cvt_f32_ubyte1_e32 v61, v147
	v_cvt_f32_ubyte0_e32 v60, v147
	v_pk_mul_f32 v[60:61], v[60:61], s[6:7] op_sel_hi:[1,0]
	s_nop 0
	v_pk_mul_f32 v[60:61], v[52:53], v[60:61]
	v_cvt_f32_ubyte3_e32 v53, v147
	v_cvt_f32_ubyte2_e32 v52, v147
	v_pk_mul_f32 v[52:53], v[52:53], s[6:7] op_sel_hi:[1,0]
	s_nop 0
	v_pk_mul_f32 v[62:63], v[54:55], v[52:53]
	v_cvt_pk_bf16_f32 v52, v56, v57
	v_cvt_pk_bf16_f32 v53, v58, v59
	v_cvt_pk_bf16_f32 v54, v60, v61
	v_cvt_pk_bf16_f32 v55, v62, v63
	global_store_dwordx4 v[64:65], v[52:55], off offset:256
	s_nop 1
	v_cvt_f32_ubyte1_e32 v53, v140
	v_cvt_f32_ubyte0_e32 v52, v140
	v_pk_mul_f32 v[52:53], v[52:53], s[6:7] op_sel_hi:[1,0]
	s_nop 0
	v_pk_mul_f32 v[48:49], v[48:49], v[52:53]
	v_cvt_f32_ubyte3_e32 v53, v140
	v_cvt_f32_ubyte2_e32 v52, v140
	v_pk_mul_f32 v[52:53], v[52:53], s[6:7] op_sel_hi:[1,0]
	s_nop 0
	v_pk_mul_f32 v[50:51], v[50:51], v[52:53]
	v_cvt_f32_ubyte1_e32 v53, v141
	v_cvt_f32_ubyte0_e32 v52, v141
	v_pk_mul_f32 v[52:53], v[52:53], s[6:7] op_sel_hi:[1,0]
	s_nop 0
	v_pk_mul_f32 v[52:53], v[44:45], v[52:53]
	v_cvt_f32_ubyte3_e32 v45, v141
	v_cvt_f32_ubyte2_e32 v44, v141
	v_pk_mul_f32 v[44:45], v[44:45], s[6:7] op_sel_hi:[1,0]
	s_nop 0
	v_pk_mul_f32 v[54:55], v[46:47], v[44:45]
	v_cvt_pk_bf16_f32 v44, v48, v49
	v_add_co_u32_e32 v48, vcc, s10, v2
	v_cvt_pk_bf16_f32 v45, v50, v51
	v_cvt_pk_bf16_f32 v46, v52, v53
	v_cvt_pk_bf16_f32 v47, v54, v55
	v_addc_co_u32_e32 v49, vcc, 0, v3, vcc
	global_store_dwordx4 v[48:49], v[44:47], off
	s_mov_b32 s10, s12
	s_nop 0
	v_cvt_f32_ubyte1_e32 v45, v142
	v_cvt_f32_ubyte0_e32 v44, v142
	v_pk_mul_f32 v[44:45], v[44:45], s[6:7] op_sel_hi:[1,0]
	s_nop 0
	v_pk_mul_f32 v[40:41], v[40:41], v[44:45]
	v_cvt_f32_ubyte3_e32 v45, v142
	v_cvt_f32_ubyte2_e32 v44, v142
	v_pk_mul_f32 v[44:45], v[44:45], s[6:7] op_sel_hi:[1,0]
	s_nop 0
	v_pk_mul_f32 v[42:43], v[42:43], v[44:45]
	v_cvt_f32_ubyte1_e32 v45, v143
	v_cvt_f32_ubyte0_e32 v44, v143
	v_pk_mul_f32 v[44:45], v[44:45], s[6:7] op_sel_hi:[1,0]
	s_nop 0
	v_pk_mul_f32 v[44:45], v[36:37], v[44:45]
	v_cvt_f32_ubyte3_e32 v37, v143
	v_cvt_f32_ubyte2_e32 v36, v143
	v_pk_mul_f32 v[36:37], v[36:37], s[6:7] op_sel_hi:[1,0]
	s_nop 0
	v_pk_mul_f32 v[46:47], v[38:39], v[36:37]
	v_cvt_pk_bf16_f32 v36, v40, v41
	v_cvt_pk_bf16_f32 v37, v42, v43
	v_cvt_pk_bf16_f32 v38, v44, v45
	v_cvt_pk_bf16_f32 v39, v46, v47
	global_store_dwordx4 v[48:49], v[36:39], off offset:256
	s_nop 1
	v_cvt_f32_ubyte1_e32 v37, v132
	v_cvt_f32_ubyte0_e32 v36, v132
	v_pk_mul_f32 v[36:37], v[36:37], s[6:7] op_sel_hi:[1,0]
	s_nop 0
	v_pk_mul_f32 v[32:33], v[32:33], v[36:37]
	v_cvt_f32_ubyte3_e32 v37, v132
	v_cvt_f32_ubyte2_e32 v36, v132
	v_pk_mul_f32 v[36:37], v[36:37], s[6:7] op_sel_hi:[1,0]
	s_nop 0
	v_pk_mul_f32 v[34:35], v[34:35], v[36:37]
	v_cvt_f32_ubyte1_e32 v37, v133
	v_cvt_f32_ubyte0_e32 v36, v133
	v_pk_mul_f32 v[36:37], v[36:37], s[6:7] op_sel_hi:[1,0]
	s_nop 0
	v_pk_mul_f32 v[36:37], v[28:29], v[36:37]
	v_cvt_f32_ubyte3_e32 v29, v133
	v_cvt_f32_ubyte2_e32 v28, v133
	v_pk_mul_f32 v[28:29], v[28:29], s[6:7] op_sel_hi:[1,0]
	s_nop 0
	v_pk_mul_f32 v[38:39], v[30:31], v[28:29]
	v_cvt_pk_bf16_f32 v28, v32, v33
	v_add_co_u32_e32 v32, vcc, s8, v2
	v_cvt_pk_bf16_f32 v29, v34, v35
	v_cvt_pk_bf16_f32 v30, v36, v37
	v_cvt_pk_bf16_f32 v31, v38, v39
	v_addc_co_u32_e32 v33, vcc, 0, v3, vcc
	global_store_dwordx4 v[32:33], v[28:31], off
	s_mov_b32 s8, 0x160000
	s_nop 0
	v_cvt_f32_ubyte1_e32 v29, v134
	v_cvt_f32_ubyte0_e32 v28, v134
	v_pk_mul_f32 v[28:29], v[28:29], s[6:7] op_sel_hi:[1,0]
	s_nop 0
	v_pk_mul_f32 v[24:25], v[24:25], v[28:29]
	v_cvt_f32_ubyte3_e32 v29, v134
	v_cvt_f32_ubyte2_e32 v28, v134
	v_pk_mul_f32 v[28:29], v[28:29], s[6:7] op_sel_hi:[1,0]
	s_nop 0
	v_pk_mul_f32 v[26:27], v[26:27], v[28:29]
	v_cvt_f32_ubyte1_e32 v29, v135
	v_cvt_f32_ubyte0_e32 v28, v135
	v_pk_mul_f32 v[28:29], v[28:29], s[6:7] op_sel_hi:[1,0]
	s_nop 0
	v_pk_mul_f32 v[28:29], v[20:21], v[28:29]
	v_cvt_f32_ubyte3_e32 v21, v135
	v_cvt_f32_ubyte2_e32 v20, v135
	v_pk_mul_f32 v[20:21], v[20:21], s[6:7] op_sel_hi:[1,0]
	s_nop 0
	v_pk_mul_f32 v[30:31], v[22:23], v[20:21]
	v_cvt_pk_bf16_f32 v20, v24, v25
	v_cvt_pk_bf16_f32 v21, v26, v27
	v_cvt_pk_bf16_f32 v22, v28, v29
	v_cvt_pk_bf16_f32 v23, v30, v31
	global_store_dwordx4 v[32:33], v[20:23], off offset:256
	s_nop 1
	v_cvt_f32_ubyte1_e32 v21, v136
	v_cvt_f32_ubyte0_e32 v20, v136
	v_pk_mul_f32 v[20:21], v[20:21], s[6:7] op_sel_hi:[1,0]
	s_nop 0
	v_pk_mul_f32 v[16:17], v[16:17], v[20:21]
	v_cvt_f32_ubyte3_e32 v21, v136
	v_cvt_f32_ubyte2_e32 v20, v136
	v_pk_mul_f32 v[20:21], v[20:21], s[6:7] op_sel_hi:[1,0]
	s_nop 0
	v_pk_mul_f32 v[18:19], v[18:19], v[20:21]
	v_cvt_f32_ubyte1_e32 v21, v137
	v_cvt_f32_ubyte0_e32 v20, v137
	v_pk_mul_f32 v[20:21], v[20:21], s[6:7] op_sel_hi:[1,0]
	s_nop 0
	v_pk_mul_f32 v[20:21], v[12:13], v[20:21]
	v_cvt_f32_ubyte3_e32 v13, v137
	v_cvt_f32_ubyte2_e32 v12, v137
	v_pk_mul_f32 v[12:13], v[12:13], s[6:7] op_sel_hi:[1,0]
	s_nop 0
	v_pk_mul_f32 v[22:23], v[14:15], v[12:13]
	v_cvt_pk_bf16_f32 v12, v16, v17
	v_add_co_u32_e32 v16, vcc, s8, v2
	v_cvt_f32_ubyte2_e32 v2, v138
	s_nop 0
	v_addc_co_u32_e32 v17, vcc, 0, v3, vcc
	v_cvt_f32_ubyte3_e32 v3, v138
	v_pk_mul_f32 v[2:3], v[2:3], s[6:7] op_sel_hi:[1,0]
	v_cvt_pk_bf16_f32 v13, v18, v19
	v_pk_mul_f32 v[10:11], v[10:11], v[2:3]
	v_cvt_f32_ubyte1_e32 v3, v138
	v_cvt_f32_ubyte0_e32 v2, v138
	v_pk_mul_f32 v[2:3], v[2:3], s[6:7] op_sel_hi:[1,0]
	v_cvt_pk_bf16_f32 v14, v20, v21
	v_pk_mul_f32 v[2:3], v[8:9], v[2:3]
	v_cvt_f32_ubyte1_e32 v9, v139
	v_cvt_f32_ubyte0_e32 v8, v139
	v_pk_mul_f32 v[8:9], v[8:9], s[6:7] op_sel_hi:[1,0]
	v_cvt_pk_bf16_f32 v15, v22, v23
	v_pk_mul_f32 v[4:5], v[4:5], v[8:9]
	v_cvt_f32_ubyte3_e32 v9, v139
	v_cvt_f32_ubyte2_e32 v8, v139
	v_pk_mul_f32 v[8:9], v[8:9], s[6:7] op_sel_hi:[1,0]
	v_cvt_pk_bf16_f32 v2, v2, v3
	v_pk_mul_f32 v[6:7], v[6:7], v[8:9]
	v_cvt_pk_bf16_f32 v3, v10, v11
	v_cvt_pk_bf16_f32 v4, v4, v5
	v_cvt_pk_bf16_f32 v5, v6, v7
	s_and_b64 vcc, exec, s[4:5]
	s_mov_b32 s8, s47
	global_store_dwordx4 v[16:17], v[12:15], off
	global_store_dwordx4 v[16:17], v[2:5], off offset:256
	s_cbranch_vccnz .LBB0_788
.LBB0_778:
	v_readlane_b32 s98, v255, 4
	s_nop 3
	s_cmp_lg_u32 s98, 0
	s_cbranch_scc0 .Lprio_skip_br
	s_setprio 1

; #define PG8_STAGE(bufoff, gbase, voff) do { unsigned _g = (gbase); asm volatile("" : "+s"(_g));   _Pragma("unroll") for (int _i = 0; _i < 2; ++_i) \
;         __builtin_amdgcn_global_load_lds((const unsigned*)(wsb + (size_t)(unsigned)(_g + (voff)[_i])), (LAS unsigned*)(lds + (bufoff) + ldsw + _i * 8192), 16, 0, 0); } while (0)
; #define PG8_WAIT_V(n) asm volatile("s_waitcnt vmcnt(" #n ")" ::: "memory")
; #define PG8_WAIT_L(n) asm volatile("s_waitcnt lgkmcnt(" #n ")" ::: "memory")
; #define PG8_BAR __builtin_amdgcn_s_barrier()
; #define PG8_SCHED __builtin_amdgcn_sched_barrier(0)
;     ...
;             PG8_LDB(B0, 0, 0); PG8_LDB(B1, 0, 1); PG8_SCHED; PG8_LDA(At, 0, 0); PG8_STAGE(PG8_SA(1, 1), a1 + hstep, voffA);
;             PG8_WAIT_V(8); PG8_WAIT_L(0); PG8_BAR; PG8_MMA(0, 0, At, B0); PG8_MMA(0, 1, At, B1); PG8_BAR; PG8_SCHED;
;             PG8_LDA(At, 0, 1); PG8_STAGE(PG8_SB(0, 0), b2, voffB); PG8_STAGE(PG8_SB(0, 1), b2 + hstep, voffB); PG8_STAGE(PG8_SA(0, 0), a2, voffA);
.LBB0_785:
	v_readfirstlane_b32 s100, v196
	v_readfirstlane_b32 s101, v197
	s_nop 1
	s_sub_u32 s100, s100, 0x10000000
	s_subb_u32 s101, s101, 0
	s_add_i32 s11, s86, s89
	s_add_i32 s8, s11, 0x100
	s_add_i32 s9, s88, s89
	s_cmpk_eq_i32 s89, 0x1f00
	s_cselect_b32 s10, s46, s8
	s_cselect_b32 s9, s47, s9
	s_add_i32 s91, 0, 0x10000
	v_add_u32_e32 v0, s91, v206
	s_add_i32 s96, 0, 0x14000
	ds_read_b128 v[132:135], v0
	ds_read_b128 v[136:139], v0 offset:1024
	ds_read_b128 v[140:143], v0 offset:2048
	ds_read_b128 v[144:147], v0 offset:3072
	v_add_u32_e32 v0, s96, v206
	ds_read_b128 v[148:151], v0
	ds_read_b128 v[152:155], v0 offset:1024
	ds_read_b128 v[156:159], v0 offset:2048
	ds_read_b128 v[160:163], v0 offset:3072
	s_add_i32 s8, s10, 0x80
	s_add_i32 s11, s11, 0x100080
	ds_read_b128 v[164:167], v207
	ds_read_b128 v[168:171], v207 offset:1024
	ds_read_b128 v[172:175], v207 offset:2048
	ds_read_b128 v[176:179], v207 offset:3072
	ds_read_b128 v[180:183], v207 offset:4096
	ds_read_b128 v[184:187], v207 offset:5120
	ds_read_b128 v[188:191], v207 offset:6144
	ds_read_b128 v[192:195], v207 offset:7168
	s_add_i32 m0, s23, 0xc000
	s_add_i32 vcc_lo, s11, 0x10000000
	s_add_u32 vcc_lo, s100, vcc_lo
	s_addc_u32 vcc_hi, s101, 0
	global_load_lds_dwordx4 v202, vcc
	s_add_i32 m0, s23, 0xe000
	s_nop 0
	global_load_lds_dwordx4 v204, vcc
	s_waitcnt vmcnt(8)
	s_waitcnt lgkmcnt(0)
	s_barrier
	s_waitcnt lgkmcnt(0)
	v_mfma_f32_16x16x32_bf16 v[128:131], v[132:135], v[164:167], v[128:131]
	v_mfma_f32_16x16x32_bf16 v[124:127], v[140:143], v[164:167], v[124:127]
	v_mfma_f32_16x16x32_bf16 v[112:115], v[132:135], v[172:175], v[112:115]
	v_mfma_f32_16x16x32_bf16 v[108:111], v[140:143], v[172:175], v[108:111]
	v_mfma_f32_16x16x32_bf16 v[96:99], v[132:135], v[180:183], v[96:99]
	v_mfma_f32_16x16x32_bf16 v[92:95], v[140:143], v[180:183], v[92:95]
	v_mfma_f32_16x16x32_bf16 v[80:83], v[132:135], v[188:191], v[80:83]
	v_mfma_f32_16x16x32_bf16 v[76:79], v[140:143], v[188:191], v[76:79]
	v_mfma_f32_16x16x32_bf16 v[128:131], v[136:139], v[168:171], v[128:131]
	v_mfma_f32_16x16x32_bf16 v[124:127], v[144:147], v[168:171], v[124:127]
	v_mfma_f32_16x16x32_bf16 v[112:115], v[136:139], v[176:179], v[112:115]
	v_mfma_f32_16x16x32_bf16 v[108:111], v[144:147], v[176:179], v[108:111]
	v_mfma_f32_16x16x32_bf16 v[96:99], v[136:139], v[184:187], v[96:99]
	v_mfma_f32_16x16x32_bf16 v[92:95], v[144:147], v[184:187], v[92:95]
	v_mfma_f32_16x16x32_bf16 v[80:83], v[136:139], v[192:195], v[80:83]
	v_mfma_f32_16x16x32_bf16 v[76:79], v[144:147], v[192:195], v[76:79]
	v_mfma_f32_16x16x32_bf16 v[120:123], v[148:151], v[164:167], v[120:123]
	v_mfma_f32_16x16x32_bf16 v[116:119], v[156:159], v[164:167], v[116:119]
	v_mfma_f32_16x16x32_bf16 v[104:107], v[148:151], v[172:175], v[104:107]
	v_mfma_f32_16x16x32_bf16 v[100:103], v[156:159], v[172:175], v[100:103]
	v_mfma_f32_16x16x32_bf16 v[88:91], v[148:151], v[180:183], v[88:91]
	v_mfma_f32_16x16x32_bf16 v[84:87], v[156:159], v[180:183], v[84:87]
	v_mfma_f32_16x16x32_bf16 v[72:75], v[148:151], v[188:191], v[72:75]
	v_mfma_f32_16x16x32_bf16 v[68:71], v[156:159], v[188:191], v[68:71]
	v_mfma_f32_16x16x32_bf16 v[120:123], v[152:155], v[168:171], v[120:123]
	v_mfma_f32_16x16x32_bf16 v[116:119], v[160:163], v[168:171], v[116:119]
	v_mfma_f32_16x16x32_bf16 v[104:107], v[152:155], v[176:179], v[104:107]
	v_mfma_f32_16x16x32_bf16 v[100:103], v[160:163], v[176:179], v[100:103]
	v_mfma_f32_16x16x32_bf16 v[88:91], v[152:155], v[184:187], v[88:91]
	v_mfma_f32_16x16x32_bf16 v[84:87], v[160:163], v[184:187], v[84:87]
	v_mfma_f32_16x16x32_bf16 v[72:75], v[152:155], v[192:195], v[72:75]
	v_mfma_f32_16x16x32_bf16 v[68:71], v[160:163], v[192:195], v[68:71]
	s_barrier
	s_mov_b32 s11, s9
	ds_read_b128 v[164:167], v207 offset:16384
	ds_read_b128 v[168:171], v207 offset:17408
	ds_read_b128 v[172:175], v207 offset:18432
	ds_read_b128 v[176:179], v207 offset:19456
	ds_read_b128 v[180:183], v207 offset:20480
	ds_read_b128 v[184:187], v207 offset:21504
	ds_read_b128 v[188:191], v207 offset:22528
	ds_read_b128 v[192:195], v207 offset:23552
	s_add_i32 s91, s91, s7
	s_add_i32 vcc_lo, s11, 0x10000000
	s_add_u32 vcc_lo, s100, vcc_lo
	s_addc_u32 vcc_hi, s101, 0
	s_mov_b32 m0, s91
	s_nop 0
	global_load_lds_dwordx4 v203, vcc
	s_add_i32 m0, s91, 0x2000
	s_add_i32 s11, s9, 0x100000
	global_load_lds_dwordx4 v205, vcc
	s_add_i32 s91, s96, s7
	s_add_i32 vcc_lo, s11, 0x10000000
	s_add_u32 vcc_lo, s100, vcc_lo
	s_addc_u32 vcc_hi, s101, 0
	s_mov_b32 m0, s91
	s_nop 0
	global_load_lds_dwordx4 v203, vcc
	s_add_i32 m0, s91, 0x2000
	s_mov_b32 s11, s10
	global_load_lds_dwordx4 v205, vcc
	s_mov_b32 m0, s23
	s_add_i32 vcc_lo, s11, 0x10000000
	s_add_u32 vcc_lo, s100, vcc_lo
	s_addc_u32 vcc_hi, s101, 0
	global_load_lds_dwordx4 v202, vcc
	s_mov_b32 m0, s24
	s_nop 0
	global_load_lds_dwordx4 v204, vcc
	s_waitcnt vmcnt(8)
	s_waitcnt lgkmcnt(0)
	s_barrier
; #define PG8_STAGE(bufoff, gbase, voff) do { unsigned _g = (gbase); asm volatile("" : "+s"(_g));   _Pragma("unroll") for (int _i = 0; _i < 2; ++_i) \
;         __builtin_amdgcn_global_load_lds((const unsigned*)(wsb + (size_t)(unsigned)(_g + (voff)[_i])), (LAS unsigned*)(lds + (bufoff) + ldsw + _i * 8192), 16, 0, 0); } while (0)
; #define PG8_WAIT_V(n) asm volatile("s_waitcnt vmcnt(" #n ")" ::: "memory")
; #define PG8_WAIT_L(n) asm volatile("s_waitcnt lgkmcnt(" #n ")" ::: "memory")
; #define PG8_BAR __builtin_amdgcn_s_barrier()
; #define PG8_SCHED __builtin_amdgcn_sched_barrier(0)
;     ...
;             PG8_WAIT_V(8); PG8_WAIT_L(0); PG8_BAR; PG8_MMA(1, 0, At, B0); PG8_MMA(1, 1, At, B1); PG8_BAR; PG8_SCHED;
;             PG8_LDB(B0, 1, 0); PG8_LDB(B1, 1, 1); PG8_SCHED; PG8_LDA(At, 1, 0); PG8_STAGE(PG8_SA(0, 1), a2 + hstep, voffA);
;             PG8_WAIT_V(8); PG8_WAIT_L(0); PG8_BAR; PG8_MMA(0, 0, At, B0); PG8_MMA(0, 1, At, B1); PG8_BAR; PG8_SCHED;
	s_waitcnt lgkmcnt(0)
	v_mfma_f32_16x16x32_bf16 v[64:67], v[132:135], v[164:167], v[64:67]
	v_mfma_f32_16x16x32_bf16 v[60:63], v[140:143], v[164:167], v[60:63]
	v_mfma_f32_16x16x32_bf16 v[48:51], v[132:135], v[172:175], v[48:51]
	v_mfma_f32_16x16x32_bf16 v[44:47], v[140:143], v[172:175], v[44:47]
	v_mfma_f32_16x16x32_bf16 v[32:35], v[132:135], v[180:183], v[32:35]
	v_mfma_f32_16x16x32_bf16 v[28:31], v[140:143], v[180:183], v[28:31]
	v_mfma_f32_16x16x32_bf16 v[16:19], v[132:135], v[188:191], v[16:19]
	v_mfma_f32_16x16x32_bf16 v[12:15], v[140:143], v[188:191], v[12:15]
	v_mfma_f32_16x16x32_bf16 v[64:67], v[136:139], v[168:171], v[64:67]
	v_mfma_f32_16x16x32_bf16 v[60:63], v[144:147], v[168:171], v[60:63]
	v_mfma_f32_16x16x32_bf16 v[48:51], v[136:139], v[176:179], v[48:51]
	v_mfma_f32_16x16x32_bf16 v[44:47], v[144:147], v[176:179], v[44:47]
	v_mfma_f32_16x16x32_bf16 v[32:35], v[136:139], v[184:187], v[32:35]
	v_mfma_f32_16x16x32_bf16 v[28:31], v[144:147], v[184:187], v[28:31]
	v_mfma_f32_16x16x32_bf16 v[16:19], v[136:139], v[192:195], v[16:19]
	v_mfma_f32_16x16x32_bf16 v[12:15], v[144:147], v[192:195], v[12:15]
	v_mfma_f32_16x16x32_bf16 v[56:59], v[148:151], v[164:167], v[56:59]
	v_mfma_f32_16x16x32_bf16 v[52:55], v[156:159], v[164:167], v[52:55]
	v_mfma_f32_16x16x32_bf16 v[40:43], v[148:151], v[172:175], v[40:43]
	v_mfma_f32_16x16x32_bf16 v[36:39], v[156:159], v[172:175], v[36:39]
	v_mfma_f32_16x16x32_bf16 v[24:27], v[148:151], v[180:183], v[24:27]
	v_mfma_f32_16x16x32_bf16 v[20:23], v[156:159], v[180:183], v[20:23]
	v_mfma_f32_16x16x32_bf16 v[8:11], v[148:151], v[188:191], v[8:11]
	v_mfma_f32_16x16x32_bf16 v[2:5], v[156:159], v[188:191], v[4:7]
	v_mfma_f32_16x16x32_bf16 v[56:59], v[152:155], v[168:171], v[56:59]
	v_mfma_f32_16x16x32_bf16 v[52:55], v[160:163], v[168:171], v[52:55]
	v_mfma_f32_16x16x32_bf16 v[40:43], v[152:155], v[176:179], v[40:43]
	v_mfma_f32_16x16x32_bf16 v[36:39], v[160:163], v[176:179], v[36:39]
	v_mfma_f32_16x16x32_bf16 v[24:27], v[152:155], v[184:187], v[24:27]
	v_mfma_f32_16x16x32_bf16 v[20:23], v[160:163], v[184:187], v[20:23]
	v_mfma_f32_16x16x32_bf16 v[8:11], v[152:155], v[192:195], v[8:11]
	v_mfma_f32_16x16x32_bf16 v[2:5], v[160:163], v[192:195], v[2:5]
	s_barrier
	s_add_i32 s11, 0, 0x18000
	v_add_u32_e32 v0, s11, v206
	s_add_i32 s91, 0, 0x1c000
	ds_read_b128 v[132:135], v0
	ds_read_b128 v[136:139], v0 offset:1024
	ds_read_b128 v[140:143], v0 offset:2048
	ds_read_b128 v[144:147], v0 offset:3072
	v_add_u32_e32 v0, s91, v206
	ds_read_b128 v[148:151], v0
	ds_read_b128 v[152:155], v0 offset:1024
	ds_read_b128 v[156:159], v0 offset:2048
	ds_read_b128 v[160:163], v0 offset:3072
	s_add_i32 s10, s10, 0x100000
	ds_read_b128 v[164:167], v207 offset:32768
	ds_read_b128 v[168:171], v207 offset:33792
	ds_read_b128 v[172:175], v207 offset:34816
	ds_read_b128 v[176:179], v207 offset:35840
	ds_read_b128 v[180:183], v207 offset:36864
	ds_read_b128 v[184:187], v207 offset:37888
	ds_read_b128 v[188:191], v207 offset:38912
	ds_read_b128 v[192:195], v207 offset:39936
	s_mov_b32 m0, s25
	s_add_i32 vcc_lo, s10, 0x10000000
	s_add_u32 vcc_lo, s100, vcc_lo
	s_addc_u32 vcc_hi, s101, 0
	global_load_lds_dwordx4 v202, vcc
	s_mov_b32 m0, s38
	s_nop 0
	global_load_lds_dwordx4 v204, vcc
	s_waitcnt vmcnt(8)
	s_waitcnt lgkmcnt(0)
	s_barrier
	s_waitcnt lgkmcnt(0)
	v_mfma_f32_16x16x32_bf16 v[128:131], v[132:135], v[164:167], v[128:131]
	v_mfma_f32_16x16x32_bf16 v[124:127], v[140:143], v[164:167], v[124:127]
	v_mfma_f32_16x16x32_bf16 v[112:115], v[132:135], v[172:175], v[112:115]
	v_mfma_f32_16x16x32_bf16 v[108:111], v[140:143], v[172:175], v[108:111]
	v_mfma_f32_16x16x32_bf16 v[96:99], v[132:135], v[180:183], v[96:99]
	v_mfma_f32_16x16x32_bf16 v[92:95], v[140:143], v[180:183], v[92:95]
	v_mfma_f32_16x16x32_bf16 v[80:83], v[132:135], v[188:191], v[80:83]
	v_mfma_f32_16x16x32_bf16 v[76:79], v[140:143], v[188:191], v[76:79]
	v_mfma_f32_16x16x32_bf16 v[128:131], v[136:139], v[168:171], v[128:131]
	v_mfma_f32_16x16x32_bf16 v[124:127], v[144:147], v[168:171], v[124:127]
	v_mfma_f32_16x16x32_bf16 v[112:115], v[136:139], v[176:179], v[112:115]
	v_mfma_f32_16x16x32_bf16 v[108:111], v[144:147], v[176:179], v[108:111]
	v_mfma_f32_16x16x32_bf16 v[96:99], v[136:139], v[184:187], v[96:99]
	v_mfma_f32_16x16x32_bf16 v[92:95], v[144:147], v[184:187], v[92:95]
	v_mfma_f32_16x16x32_bf16 v[80:83], v[136:139], v[192:195], v[80:83]
	v_mfma_f32_16x16x32_bf16 v[76:79], v[144:147], v[192:195], v[76:79]
	v_mfma_f32_16x16x32_bf16 v[120:123], v[148:151], v[164:167], v[120:123]
	v_mfma_f32_16x16x32_bf16 v[116:119], v[156:159], v[164:167], v[116:119]
	v_mfma_f32_16x16x32_bf16 v[104:107], v[148:151], v[172:175], v[104:107]
	v_mfma_f32_16x16x32_bf16 v[100:103], v[156:159], v[172:175], v[100:103]
	v_mfma_f32_16x16x32_bf16 v[88:91], v[148:151], v[180:183], v[88:91]
	v_mfma_f32_16x16x32_bf16 v[84:87], v[156:159], v[180:183], v[84:87]
	v_mfma_f32_16x16x32_bf16 v[72:75], v[148:151], v[188:191], v[72:75]
	v_mfma_f32_16x16x32_bf16 v[68:71], v[156:159], v[188:191], v[68:71]
	v_mfma_f32_16x16x32_bf16 v[120:123], v[152:155], v[168:171], v[120:123]
	v_mfma_f32_16x16x32_bf16 v[116:119], v[160:163], v[168:171], v[116:119]
	v_mfma_f32_16x16x32_bf16 v[104:107], v[152:155], v[176:179], v[104:107]
	v_mfma_f32_16x16x32_bf16 v[100:103], v[160:163], v[176:179], v[100:103]
	v_mfma_f32_16x16x32_bf16 v[88:91], v[152:155], v[184:187], v[88:91]
	v_mfma_f32_16x16x32_bf16 v[84:87], v[160:163], v[184:187], v[84:87]
	v_mfma_f32_16x16x32_bf16 v[72:75], v[152:155], v[192:195], v[72:75]
	v_mfma_f32_16x16x32_bf16 v[68:71], v[160:163], v[192:195], v[68:71]
	s_barrier
; __device__ __forceinline__ int lane_id_hw() { int l; asm volatile("v_mbcnt_lo_u32_b32 %0, -1, 0\n\tv_mbcnt_hi_u32_b32 %0, -1, %0" : "=v"(l)); return l; }
; #define PG8_STAGE(bufoff, gbase, voff) do { unsigned _g = (gbase); asm volatile("" : "+s"(_g));   _Pragma("unroll") for (int _i = 0; _i < 2; ++_i) \
;         __builtin_amdgcn_global_load_lds((const unsigned*)(wsb + (size_t)(unsigned)(_g + (voff)[_i])), (LAS unsigned*)(lds + (bufoff) + ldsw + _i * 8192), 16, 0, 0); } while (0)
; #define PG8_WAIT_V(n) asm volatile("s_waitcnt vmcnt(" #n ")" ::: "memory")
; #define PG8_WAIT_L(n) asm volatile("s_waitcnt lgkmcnt(" #n ")" ::: "memory")
; #define PG8_BAR __builtin_amdgcn_s_barrier()
; #define PG8_SCHED __builtin_amdgcn_sched_barrier(0)
;     ...
;         for (int t = 0; t < nt; t += 2) {
;             if constexpr (Epi::HAS_MID) { if (t == Epi::MID0 || t == Epi::MID1) { const int l2 = lane_id_hw(); E.mid(acc, cur, t == Epi::MID0 ? 0 : 1, wr, wc, l2 & 15, l2 >> 4); } }
;     ...
;             PG8_LDA(At, 1, 1); PG8_STAGE(PG8_SB(1, 0), b3, voffB); PG8_STAGE(PG8_SB(1, 1), b3 + hstep, voffB); PG8_STAGE(PG8_SA(1, 0), a3, voffA);
;             PG8_WAIT_V(8); PG8_WAIT_L(0); PG8_BAR; PG8_MMA(1, 0, At, B0); PG8_MMA(1, 1, At, B1); PG8_BAR; PG8_SCHED;
	s_add_i32 s10, s9, 0x80
	ds_read_b128 v[164:167], v207 offset:49152
	ds_read_b128 v[168:171], v207 offset:50176
	ds_read_b128 v[172:175], v207 offset:51200
	ds_read_b128 v[176:179], v207 offset:52224
	ds_read_b128 v[180:183], v207 offset:53248
	ds_read_b128 v[184:187], v207 offset:54272
	ds_read_b128 v[188:191], v207 offset:55296
	ds_read_b128 v[192:195], v207 offset:56320
	s_add_i32 s11, s11, s7
	s_add_i32 vcc_lo, s10, 0x10000000
	s_add_u32 vcc_lo, s100, vcc_lo
	s_addc_u32 vcc_hi, s101, 0
	s_mov_b32 m0, s11
	s_nop 0
	global_load_lds_dwordx4 v203, vcc
	s_add_i32 m0, s11, 0x2000
	s_add_i32 s9, s9, 0x100080
	global_load_lds_dwordx4 v205, vcc
	s_add_i32 s10, s91, s7
	s_add_i32 vcc_lo, s9, 0x10000000
	s_add_u32 vcc_lo, s100, vcc_lo
	s_addc_u32 vcc_hi, s101, 0
	s_mov_b32 m0, s10
	s_nop 0
	global_load_lds_dwordx4 v203, vcc
	s_add_i32 m0, s10, 0x2000
	s_nop 0
	global_load_lds_dwordx4 v205, vcc
	s_mov_b32 m0, s39
	s_add_i32 vcc_lo, s8, 0x10000000
	s_add_u32 vcc_lo, s100, vcc_lo
	s_addc_u32 vcc_hi, s101, 0
	global_load_lds_dwordx4 v202, vcc
	s_mov_b32 m0, s44
	s_nop 0
	global_load_lds_dwordx4 v204, vcc
	s_waitcnt vmcnt(8)
	s_waitcnt lgkmcnt(0)
	s_barrier
	s_waitcnt lgkmcnt(0)
	v_mfma_f32_16x16x32_bf16 v[64:67], v[132:135], v[164:167], v[64:67]
	v_mfma_f32_16x16x32_bf16 v[60:63], v[140:143], v[164:167], v[60:63]
	v_mfma_f32_16x16x32_bf16 v[48:51], v[132:135], v[172:175], v[48:51]
	v_mfma_f32_16x16x32_bf16 v[44:47], v[140:143], v[172:175], v[44:47]
	v_mfma_f32_16x16x32_bf16 v[32:35], v[132:135], v[180:183], v[32:35]
	v_mfma_f32_16x16x32_bf16 v[28:31], v[140:143], v[180:183], v[28:31]
	v_mfma_f32_16x16x32_bf16 v[16:19], v[132:135], v[188:191], v[16:19]
	v_mfma_f32_16x16x32_bf16 v[12:15], v[140:143], v[188:191], v[12:15]
	v_mfma_f32_16x16x32_bf16 v[64:67], v[136:139], v[168:171], v[64:67]
	v_mfma_f32_16x16x32_bf16 v[60:63], v[144:147], v[168:171], v[60:63]
	v_mfma_f32_16x16x32_bf16 v[48:51], v[136:139], v[176:179], v[48:51]
	v_mfma_f32_16x16x32_bf16 v[44:47], v[144:147], v[176:179], v[44:47]
	v_mfma_f32_16x16x32_bf16 v[32:35], v[136:139], v[184:187], v[32:35]
	v_mfma_f32_16x16x32_bf16 v[28:31], v[144:147], v[184:187], v[28:31]
	v_mfma_f32_16x16x32_bf16 v[16:19], v[136:139], v[192:195], v[16:19]
	v_mfma_f32_16x16x32_bf16 v[12:15], v[144:147], v[192:195], v[12:15]
	v_mfma_f32_16x16x32_bf16 v[56:59], v[148:151], v[164:167], v[56:59]
	v_mfma_f32_16x16x32_bf16 v[52:55], v[156:159], v[164:167], v[52:55]
	v_mfma_f32_16x16x32_bf16 v[40:43], v[148:151], v[172:175], v[40:43]
	v_mfma_f32_16x16x32_bf16 v[36:39], v[156:159], v[172:175], v[36:39]
	v_mfma_f32_16x16x32_bf16 v[24:27], v[148:151], v[180:183], v[24:27]
	v_mfma_f32_16x16x32_bf16 v[20:23], v[156:159], v[180:183], v[20:23]
	v_mfma_f32_16x16x32_bf16 v[6:9], v[148:151], v[188:191], v[8:11]
	v_mfma_f32_16x16x32_bf16 v[2:5], v[156:159], v[188:191], v[2:5]
	v_mfma_f32_16x16x32_bf16 v[56:59], v[152:155], v[168:171], v[56:59]
	v_mfma_f32_16x16x32_bf16 v[52:55], v[160:163], v[168:171], v[52:55]
	v_mfma_f32_16x16x32_bf16 v[40:43], v[152:155], v[176:179], v[40:43]
	v_mfma_f32_16x16x32_bf16 v[36:39], v[160:163], v[176:179], v[36:39]
	v_mfma_f32_16x16x32_bf16 v[24:27], v[152:155], v[184:187], v[24:27]
	v_mfma_f32_16x16x32_bf16 v[20:23], v[160:163], v[184:187], v[20:23]
	v_mfma_f32_16x16x32_bf16 v[8:11], v[152:155], v[192:195], v[6:9]
	v_mfma_f32_16x16x32_bf16 v[4:7], v[160:163], v[192:195], v[2:5]
	s_barrier
	s_add_i32 s8, s90, 2
	s_addk_i32 s89, 0x100
	s_cmp_gt_u32 s90, 61
	s_cbranch_scc1 .LBB0_777
	s_mov_b32 s90, s8
	s_cmp_lt_i32 s90, 48
	s_cbranch_scc1 .LBB0_781
